# P0: RMSNorm gain vector loaded once per wave (not per row behind store drains), w_up gain values loaded once per transpose item, all 16 source loads of a transpose item in flight
# baseline (speedup 1.0000x reference)
; #define LAS __attribute__((address_space(3)))
; #define LDS_WAIT() asm volatile("s_waitcnt lgkmcnt(0)" ::: "memory")
; __device__ __forceinline__ void transpose_item(const float* __restrict__ W, int N, int src_n0, int n_valid, bf16_t* __restrict__ WT, int Kd, int dst_row0, int k0, ...
;     const int c4 = (lane & 15) * 4, kr = lane >> 4;
; #pragma unroll 4
;     for (int i = 0; i < 16; ++i) { const int kk = 4 * i + kr;
;         f32x4 v = {0.f, 0.f, 0.f, 0.f};
;         if (c4 < n_valid) v = *(const f32x4*)(W + (size_t)(k0 + kk) * N + src_n0 + c4);
;         LAS float* d = scr + kk * 65 + c4; d[0] = v.x; d[1] = v.y; d[2] = v.z; d[3] = v.w; }
;     LDS_WAIT();
;     const int c8 = lane & 7;
; #pragma unroll
;     for (int j = 0; j < 8; ++j) { const int n = (lane >> 3) + 8 * j; const LAS float* s = scr + (8 * c8) * 65 + n;
;         const float sc = (scale != nullptr && n < n_valid) ? scale[src_n0 + n] : 1.f;
.LBB0_14:
	v_lshl_add_u64 v[152:153], v[36:37], 0, s[0:1]
	v_lshl_add_u64 v[156:157], v[6:7], 0, s[0:1]
	v_lshl_add_u64 v[160:161], v[4:5], 0, s[0:1]
	v_lshl_add_u64 v[164:165], v[2:3], 0, s[0:1]
	global_load_dwordx4 v[152:155], v[152:153], off
	s_nop 0
	global_load_dwordx4 v[156:159], v[156:157], off
	s_nop 0
	global_load_dwordx4 v[160:163], v[160:161], off
	s_nop 0
	global_load_dwordx4 v[164:167], v[164:165], off
	s_nop 0
	s_add_u32 s0, s0, 0x4000
	s_addc_u32 s1, s1, 0
	v_lshl_add_u64 v[168:169], v[36:37], 0, s[0:1]
	v_lshl_add_u64 v[172:173], v[6:7], 0, s[0:1]
	v_lshl_add_u64 v[176:177], v[4:5], 0, s[0:1]
	v_lshl_add_u64 v[180:181], v[2:3], 0, s[0:1]
	global_load_dwordx4 v[168:171], v[168:169], off
	s_nop 0
	global_load_dwordx4 v[172:175], v[172:173], off
	s_nop 0
	global_load_dwordx4 v[176:179], v[176:177], off
	s_nop 0
	global_load_dwordx4 v[180:183], v[180:181], off
	s_nop 0
	s_add_u32 s0, s0, 0x4000
	s_addc_u32 s1, s1, 0
	v_lshl_add_u64 v[184:185], v[36:37], 0, s[0:1]
	v_lshl_add_u64 v[188:189], v[6:7], 0, s[0:1]
	v_lshl_add_u64 v[192:193], v[4:5], 0, s[0:1]
	v_lshl_add_u64 v[196:197], v[2:3], 0, s[0:1]
	global_load_dwordx4 v[184:187], v[184:185], off
	s_nop 0
	global_load_dwordx4 v[188:191], v[188:189], off
	s_nop 0
	global_load_dwordx4 v[192:195], v[192:193], off
	s_nop 0
	global_load_dwordx4 v[196:199], v[196:197], off
	s_nop 0
	s_add_u32 s0, s0, 0x4000
	s_addc_u32 s1, s1, 0
	v_lshl_add_u64 v[200:201], v[36:37], 0, s[0:1]
	v_lshl_add_u64 v[204:205], v[6:7], 0, s[0:1]
	v_lshl_add_u64 v[208:209], v[4:5], 0, s[0:1]
	v_lshl_add_u64 v[212:213], v[2:3], 0, s[0:1]
	global_load_dwordx4 v[200:203], v[200:201], off
	s_nop 0
	global_load_dwordx4 v[204:207], v[204:205], off
	s_nop 0
	global_load_dwordx4 v[208:211], v[208:209], off
	s_nop 0
	global_load_dwordx4 v[212:215], v[212:213], off
	s_nop 0
	s_add_u32 s0, s0, 0x4000
	s_addc_u32 s1, s1, 0
	v_add_u32_e32 v74, 0x410, v14
	v_add_u32_e32 v75, 0x418, v14
	v_add_u32_e32 v76, 0x820, v14
	v_add_u32_e32 v77, 0x828, v14
	v_add_u32_e32 v78, 0xc30, v14
	v_add_u32_e32 v79, 0xc38, v14
	s_waitcnt vmcnt(15)
	ds_write2_b32 v14, v152, v153 offset1:1
	ds_write2_b32 v14, v154, v155 offset0:2 offset1:3
	s_waitcnt vmcnt(14)
	ds_write2_b32 v74, v156, v157 offset1:1
	ds_write2_b32 v75, v158, v159 offset1:1
	s_waitcnt vmcnt(13)
	ds_write2_b32 v76, v160, v161 offset1:1
	ds_write2_b32 v77, v162, v163 offset1:1
	s_waitcnt vmcnt(12)
	ds_write2_b32 v78, v164, v165 offset1:1
	ds_write2_b32 v79, v166, v167 offset1:1
	v_add_u32_e32 v14, 0x1040, v14
	v_add_u32_e32 v74, 0x410, v14
	v_add_u32_e32 v75, 0x418, v14
	v_add_u32_e32 v76, 0x820, v14
	v_add_u32_e32 v77, 0x828, v14
	v_add_u32_e32 v78, 0xc30, v14
	v_add_u32_e32 v79, 0xc38, v14
	s_waitcnt vmcnt(11)
	ds_write2_b32 v14, v168, v169 offset1:1
	ds_write2_b32 v14, v170, v171 offset0:2 offset1:3
	s_waitcnt vmcnt(10)
	ds_write2_b32 v74, v172, v173 offset1:1
	ds_write2_b32 v75, v174, v175 offset1:1
	s_waitcnt vmcnt(9)
	ds_write2_b32 v76, v176, v177 offset1:1
	ds_write2_b32 v77, v178, v179 offset1:1
	s_waitcnt vmcnt(8)
	ds_write2_b32 v78, v180, v181 offset1:1
	ds_write2_b32 v79, v182, v183 offset1:1
	v_add_u32_e32 v14, 0x1040, v14
	v_add_u32_e32 v74, 0x410, v14
	v_add_u32_e32 v75, 0x418, v14
	v_add_u32_e32 v76, 0x820, v14
	v_add_u32_e32 v77, 0x828, v14
	v_add_u32_e32 v78, 0xc30, v14
	v_add_u32_e32 v79, 0xc38, v14
	s_waitcnt vmcnt(7)
	ds_write2_b32 v14, v184, v185 offset1:1
	ds_write2_b32 v14, v186, v187 offset0:2 offset1:3
	s_waitcnt vmcnt(6)
	ds_write2_b32 v74, v188, v189 offset1:1
	ds_write2_b32 v75, v190, v191 offset1:1
	s_waitcnt vmcnt(5)
	ds_write2_b32 v76, v192, v193 offset1:1
	ds_write2_b32 v77, v194, v195 offset1:1
	s_waitcnt vmcnt(4)
	ds_write2_b32 v78, v196, v197 offset1:1
	ds_write2_b32 v79, v198, v199 offset1:1
	v_add_u32_e32 v14, 0x1040, v14
	v_add_u32_e32 v74, 0x410, v14
	v_add_u32_e32 v75, 0x418, v14
	v_add_u32_e32 v76, 0x820, v14
	v_add_u32_e32 v77, 0x828, v14
	v_add_u32_e32 v78, 0xc30, v14
	v_add_u32_e32 v79, 0xc38, v14
	s_waitcnt vmcnt(3)
	ds_write2_b32 v14, v200, v201 offset1:1
	ds_write2_b32 v14, v202, v203 offset0:2 offset1:3
	s_waitcnt vmcnt(2)
	ds_write2_b32 v74, v204, v205 offset1:1
	ds_write2_b32 v75, v206, v207 offset1:1
	s_waitcnt vmcnt(1)
	ds_write2_b32 v76, v208, v209 offset1:1
	ds_write2_b32 v77, v210, v211 offset1:1
	s_waitcnt vmcnt(0)
	ds_write2_b32 v78, v212, v213 offset1:1
	ds_write2_b32 v79, v214, v215 offset1:1
	v_add_u32_e32 v14, 0x1040, v14
	s_add_i32 s0, s45, 0xffffd080
	s_lshr_b32 s6, s0, 4
	s_lshl_b32 s0, s45, 6
	s_lshl_b32 s26, s6, 8
	s_mov_b32 s27, s7
	s_and_b32 s0, s0, 0xc0
	s_lshl_b64 s[26:27], s[26:27], 2
	s_waitcnt lgkmcnt(0)
	s_add_u32 s26, s48, s26
	v_add_u32_e32 v4, s0, v8
	s_addc_u32 s27, s49, s27
	v_ashrrev_i32_e32 v5, 31, v4
	v_mov_b32_e32 v7, 1.0
	v_mov_b32_e32 v36, 1.0
	s_and_saveexec_b64 s[28:29], s[8:9]
	s_cbranch_execz .LBB0_17
	v_lshl_add_u64 v[2:3], v[4:5], 2, s[26:27]
	global_load_dword v36, v[2:3], off

; #define LAS __attribute__((address_space(3)))
; #define LDS_WAIT() asm volatile("s_waitcnt lgkmcnt(0)" ::: "memory")
; __device__ __forceinline__ void transpose_item(const float* __restrict__ W, int N, int src_n0, int n_valid, bf16_t* __restrict__ WT, int Kd, int dst_row0, int k0, ...
;     const int c4 = (lane & 15) * 4, kr = lane >> 4;
; #pragma unroll 4
;     for (int i = 0; i < 16; ++i) { const int kk = 4 * i + kr;
;         f32x4 v = {0.f, 0.f, 0.f, 0.f};
;         if (c4 < n_valid) v = *(const f32x4*)(W + (size_t)(k0 + kk) * N + src_n0 + c4);
;         LAS float* d = scr + kk * 65 + c4; d[0] = v.x; d[1] = v.y; d[2] = v.z; d[3] = v.w; }
;     LDS_WAIT();
.LBB0_34:
	v_lshl_add_u64 v[152:153], v[36:37], 0, s[0:1]
	v_lshl_add_u64 v[156:157], v[6:7], 0, s[0:1]
	v_lshl_add_u64 v[160:161], v[4:5], 0, s[0:1]
	v_lshl_add_u64 v[164:165], v[2:3], 0, s[0:1]
	global_load_dwordx4 v[152:155], v[152:153], off
	s_nop 0
	global_load_dwordx4 v[156:159], v[156:157], off
	s_nop 0
	global_load_dwordx4 v[160:163], v[160:161], off
	s_nop 0
	global_load_dwordx4 v[164:167], v[164:165], off
	s_nop 0
	s_add_u32 s0, s0, 0x20000
	s_addc_u32 s1, s1, 0
	v_lshl_add_u64 v[168:169], v[36:37], 0, s[0:1]
	v_lshl_add_u64 v[172:173], v[6:7], 0, s[0:1]
	v_lshl_add_u64 v[176:177], v[4:5], 0, s[0:1]
	v_lshl_add_u64 v[180:181], v[2:3], 0, s[0:1]
	global_load_dwordx4 v[168:171], v[168:169], off
	s_nop 0
	global_load_dwordx4 v[172:175], v[172:173], off
	s_nop 0
	global_load_dwordx4 v[176:179], v[176:177], off
	s_nop 0
	global_load_dwordx4 v[180:183], v[180:181], off
	s_nop 0
	s_add_u32 s0, s0, 0x20000
	s_addc_u32 s1, s1, 0
	v_lshl_add_u64 v[184:185], v[36:37], 0, s[0:1]
	v_lshl_add_u64 v[188:189], v[6:7], 0, s[0:1]
	v_lshl_add_u64 v[192:193], v[4:5], 0, s[0:1]
	v_lshl_add_u64 v[196:197], v[2:3], 0, s[0:1]
	global_load_dwordx4 v[184:187], v[184:185], off
	s_nop 0
	global_load_dwordx4 v[188:191], v[188:189], off
	s_nop 0
	global_load_dwordx4 v[192:195], v[192:193], off
	s_nop 0
	global_load_dwordx4 v[196:199], v[196:197], off
	s_nop 0
	s_add_u32 s0, s0, 0x20000
	s_addc_u32 s1, s1, 0
	v_lshl_add_u64 v[200:201], v[36:37], 0, s[0:1]
	v_lshl_add_u64 v[204:205], v[6:7], 0, s[0:1]
	v_lshl_add_u64 v[208:209], v[4:5], 0, s[0:1]
	v_lshl_add_u64 v[212:213], v[2:3], 0, s[0:1]
	global_load_dwordx4 v[200:203], v[200:201], off
	s_nop 0
	global_load_dwordx4 v[204:207], v[204:205], off
	s_nop 0
	global_load_dwordx4 v[208:211], v[208:209], off
	s_nop 0
	global_load_dwordx4 v[212:215], v[212:213], off
	s_nop 0
	s_add_u32 s0, s0, 0x20000
	s_addc_u32 s1, s1, 0
	v_add_u32_e32 v74, 0x410, v14
	v_add_u32_e32 v75, 0x418, v14
	v_add_u32_e32 v76, 0x820, v14
	v_add_u32_e32 v77, 0x828, v14
	v_add_u32_e32 v78, 0xc30, v14
	v_add_u32_e32 v79, 0xc38, v14
	s_waitcnt vmcnt(15)
	ds_write2_b32 v14, v152, v153 offset1:1
	ds_write2_b32 v14, v154, v155 offset0:2 offset1:3
	s_waitcnt vmcnt(14)
	ds_write2_b32 v74, v156, v157 offset1:1
	ds_write2_b32 v75, v158, v159 offset1:1
	s_waitcnt vmcnt(13)
	ds_write2_b32 v76, v160, v161 offset1:1
	ds_write2_b32 v77, v162, v163 offset1:1
	s_waitcnt vmcnt(12)
	ds_write2_b32 v78, v164, v165 offset1:1
	ds_write2_b32 v79, v166, v167 offset1:1
	v_add_u32_e32 v14, 0x1040, v14
	v_add_u32_e32 v74, 0x410, v14
	v_add_u32_e32 v75, 0x418, v14
	v_add_u32_e32 v76, 0x820, v14
	v_add_u32_e32 v77, 0x828, v14
	v_add_u32_e32 v78, 0xc30, v14
	v_add_u32_e32 v79, 0xc38, v14
	s_waitcnt vmcnt(11)
	ds_write2_b32 v14, v168, v169 offset1:1
	ds_write2_b32 v14, v170, v171 offset0:2 offset1:3
	s_waitcnt vmcnt(10)
	ds_write2_b32 v74, v172, v173 offset1:1
	ds_write2_b32 v75, v174, v175 offset1:1
	s_waitcnt vmcnt(9)
	ds_write2_b32 v76, v176, v177 offset1:1
	ds_write2_b32 v77, v178, v179 offset1:1
	s_waitcnt vmcnt(8)
	ds_write2_b32 v78, v180, v181 offset1:1
	ds_write2_b32 v79, v182, v183 offset1:1
	v_add_u32_e32 v14, 0x1040, v14
	v_add_u32_e32 v74, 0x410, v14
	v_add_u32_e32 v75, 0x418, v14
	v_add_u32_e32 v76, 0x820, v14
	v_add_u32_e32 v77, 0x828, v14
	v_add_u32_e32 v78, 0xc30, v14
	v_add_u32_e32 v79, 0xc38, v14
	s_waitcnt vmcnt(7)
	ds_write2_b32 v14, v184, v185 offset1:1
	ds_write2_b32 v14, v186, v187 offset0:2 offset1:3
	s_waitcnt vmcnt(6)
	ds_write2_b32 v74, v188, v189 offset1:1
	ds_write2_b32 v75, v190, v191 offset1:1
	s_waitcnt vmcnt(5)
	ds_write2_b32 v76, v192, v193 offset1:1
	ds_write2_b32 v77, v194, v195 offset1:1
	s_waitcnt vmcnt(4)
	ds_write2_b32 v78, v196, v197 offset1:1
	ds_write2_b32 v79, v198, v199 offset1:1
	v_add_u32_e32 v14, 0x1040, v14
	v_add_u32_e32 v74, 0x410, v14
	v_add_u32_e32 v75, 0x418, v14
	v_add_u32_e32 v76, 0x820, v14
	v_add_u32_e32 v77, 0x828, v14
	v_add_u32_e32 v78, 0xc30, v14
	v_add_u32_e32 v79, 0xc38, v14
	s_waitcnt vmcnt(3)
	ds_write2_b32 v14, v200, v201 offset1:1
	ds_write2_b32 v14, v202, v203 offset0:2 offset1:3
	s_waitcnt vmcnt(2)
	ds_write2_b32 v74, v204, v205 offset1:1
	ds_write2_b32 v75, v206, v207 offset1:1
	s_waitcnt vmcnt(1)
	ds_write2_b32 v76, v208, v209 offset1:1
	ds_write2_b32 v77, v210, v211 offset1:1
	s_waitcnt vmcnt(0)
	ds_write2_b32 v78, v212, v213 offset1:1
	ds_write2_b32 v79, v214, v215 offset1:1
	v_add_u32_e32 v14, 0x1040, v14
	s_waitcnt lgkmcnt(0)
; __device__ __forceinline__ unsigned cvt_pk_bf16(float lo, float hi) { unsigned r; asm volatile("v_cvt_pk_bf16_f32 %0, %1, %2" : "=v"(r) : "v"(lo), "v"(hi)); return r; }
; #define LAS __attribute__((address_space(3)))
; #define LDS_WAIT() asm volatile("s_waitcnt lgkmcnt(0)" ::: "memory")
; __device__ __forceinline__ void transpose_item(const float* __restrict__ W, int N, int src_n0, int n_valid, bf16_t* __restrict__ WT, int Kd, int dst_row0, int k0, ...
;     ...
;     const int c8 = lane & 7;
; #pragma unroll
;     for (int j = 0; j < 8; ++j) { const int n = (lane >> 3) + 8 * j; const LAS float* s = scr + (8 * c8) * 65 + n;
;         const float sc = (scale != nullptr && n < n_valid) ? scale[src_n0 + n] : 1.f;
;         float ks[8];
; #pragma unroll
;         for (int i = 0; i < 8; ++i) ks[i] = (kscale != nullptr) ? kscale[k0 + 8 * c8 + i] * sc : sc;
;         u32x4 o; o.x = cvt_pk_bf16(s[0 * 65] * ks[0], s[1 * 65] * ks[1]); o.y = cvt_pk_bf16(s[2 * 65] * ks[2], s[3 * 65] * ks[3]); o.z = cvt_pk_bf16(s[4 * 65] * ks[4], s[5 * 65] * ks[5]); o.w = cvt_pk_bf16(s[6 * 65] * ks[6], s[7 * 65] * ks[7]);
;         *(u32x4*)(WT + (size_t)(dst_row0 + n) * Kd + k0 + 8 * c8) = o; }
;     LDS_WAIT();
	s_lshl_b32 s0, s45, 6
	s_lshl_b32 s1, s45, 1
	ds_read2_b32 v[2:3], v13 offset1:65
	s_and_b32 s26, s0, 0x7c0
	s_and_b32 s0, s1, 0x7fc0
	s_waitcnt lgkmcnt(0)
	v_cvt_pk_bf16_f32 v2, v2, v3
	ds_read2_b32 v[4:5], v13 offset0:130 offset1:195
	v_add_u32_e32 v14, 0x400, v13
	s_add_i32 s6, s0, 0xffffb700
	s_waitcnt lgkmcnt(0)
	v_cvt_pk_bf16_f32 v3, v4, v5
	ds_read2_b32 v[4:5], v14 offset0:4 offset1:69
	v_add_u32_e32 v58, s26, v8
	v_lshl_add_u64 v[36:37], s[6:7], 1, v[16:17]
	s_waitcnt lgkmcnt(0)
	v_cvt_pk_bf16_f32 v4, v4, v5
	ds_read2_b32 v[6:7], v14 offset0:134 offset1:199
	s_waitcnt lgkmcnt(0)
	v_cvt_pk_bf16_f32 v5, v6, v7
	v_mad_i64_i32 v[58:59], s[0:1], v58, s39, v[36:37]
	ds_read2_b32 v[6:7], v13 offset0:8 offset1:73
	global_store_dwordx4 v[58:59], v[2:5], off
	v_add_u32_e32 v58, s26, v38
	v_mad_i64_i32 v[58:59], s[0:1], v58, s39, v[36:37]
	s_waitcnt lgkmcnt(0)
	v_cvt_pk_bf16_f32 v2, v6, v7
	ds_read2_b32 v[4:5], v13 offset0:138 offset1:203
	s_waitcnt lgkmcnt(0)
	v_cvt_pk_bf16_f32 v3, v4, v5
	ds_read2_b32 v[4:5], v14 offset0:12 offset1:77
	s_waitcnt lgkmcnt(0)
	v_cvt_pk_bf16_f32 v4, v4, v5
	ds_read2_b32 v[6:7], v14 offset0:142 offset1:207
	s_waitcnt lgkmcnt(0)
	v_cvt_pk_bf16_f32 v5, v6, v7
	ds_read2_b32 v[6:7], v13 offset0:16 offset1:81
	global_store_dwordx4 v[58:59], v[2:5], off
	v_add_u32_e32 v58, s26, v39
	v_mad_i64_i32 v[58:59], s[0:1], v58, s39, v[36:37]
	s_waitcnt lgkmcnt(0)
	v_cvt_pk_bf16_f32 v2, v6, v7
	ds_read2_b32 v[4:5], v13 offset0:146 offset1:211
	s_waitcnt lgkmcnt(0)
	v_cvt_pk_bf16_f32 v3, v4, v5
	ds_read2_b32 v[4:5], v14 offset0:20 offset1:85
	s_waitcnt lgkmcnt(0)
	v_cvt_pk_bf16_f32 v4, v4, v5
	ds_read2_b32 v[6:7], v14 offset0:150 offset1:215
	s_waitcnt lgkmcnt(0)
	v_cvt_pk_bf16_f32 v5, v6, v7
	ds_read2_b32 v[6:7], v13 offset0:24 offset1:89
	global_store_dwordx4 v[58:59], v[2:5], off
	v_add_u32_e32 v58, s26, v40
	v_mad_i64_i32 v[58:59], s[0:1], v58, s39, v[36:37]
	s_waitcnt lgkmcnt(0)
	v_cvt_pk_bf16_f32 v2, v6, v7
	ds_read2_b32 v[4:5], v13 offset0:154 offset1:219
	s_waitcnt lgkmcnt(0)
	v_cvt_pk_bf16_f32 v3, v4, v5
	ds_read2_b32 v[4:5], v14 offset0:28 offset1:93
	s_waitcnt lgkmcnt(0)
	v_cvt_pk_bf16_f32 v4, v4, v5
	ds_read2_b32 v[6:7], v14 offset0:158 offset1:223
	s_waitcnt lgkmcnt(0)
	v_cvt_pk_bf16_f32 v5, v6, v7
	ds_read2_b32 v[6:7], v13 offset0:32 offset1:97
	global_store_dwordx4 v[58:59], v[2:5], off
	v_add_u32_e32 v58, s26, v41
	v_mad_i64_i32 v[58:59], s[0:1], v58, s39, v[36:37]
	s_waitcnt lgkmcnt(0)
	v_cvt_pk_bf16_f32 v2, v6, v7
	ds_read2_b32 v[4:5], v13 offset0:162 offset1:227
	s_waitcnt lgkmcnt(0)
	v_cvt_pk_bf16_f32 v3, v4, v5
	ds_read2_b32 v[4:5], v14 offset0:36 offset1:101
	s_waitcnt lgkmcnt(0)
	v_cvt_pk_bf16_f32 v4, v4, v5
	ds_read2_b32 v[6:7], v14 offset0:166 offset1:231
	s_waitcnt lgkmcnt(0)
	v_cvt_pk_bf16_f32 v5, v6, v7
	ds_read2_b32 v[6:7], v13 offset0:40 offset1:105
	global_store_dwordx4 v[58:59], v[2:5], off
	v_add_u32_e32 v58, s26, v42
	v_mad_i64_i32 v[58:59], s[0:1], v58, s39, v[36:37]
	s_waitcnt lgkmcnt(0)
	v_cvt_pk_bf16_f32 v2, v6, v7
	ds_read2_b32 v[4:5], v13 offset0:170 offset1:235
	s_waitcnt lgkmcnt(0)
	v_cvt_pk_bf16_f32 v3, v4, v5
	ds_read2_b32 v[4:5], v14 offset0:44 offset1:109
	s_waitcnt lgkmcnt(0)
	v_cvt_pk_bf16_f32 v4, v4, v5
	ds_read2_b32 v[6:7], v14 offset0:174 offset1:239
	s_waitcnt lgkmcnt(0)
	v_cvt_pk_bf16_f32 v5, v6, v7
	ds_read2_b32 v[6:7], v13 offset0:48 offset1:113
	global_store_dwordx4 v[58:59], v[2:5], off
	v_add_u32_e32 v58, s26, v43
	v_mad_i64_i32 v[58:59], s[0:1], v58, s39, v[36:37]
	s_waitcnt lgkmcnt(0)
	v_cvt_pk_bf16_f32 v2, v6, v7
	ds_read2_b32 v[4:5], v13 offset0:178 offset1:243
	s_waitcnt lgkmcnt(0)
	v_cvt_pk_bf16_f32 v3, v4, v5
	ds_read2_b32 v[4:5], v14 offset0:52 offset1:117
	s_waitcnt lgkmcnt(0)
	v_cvt_pk_bf16_f32 v4, v4, v5
	ds_read2_b32 v[6:7], v14 offset0:182 offset1:247
	s_waitcnt lgkmcnt(0)
	v_cvt_pk_bf16_f32 v5, v6, v7
	ds_read2_b32 v[6:7], v13 offset0:56 offset1:121
	global_store_dwordx4 v[58:59], v[2:5], off
	s_waitcnt lgkmcnt(0)
	s_nop 0
	v_cvt_pk_bf16_f32 v2, v6, v7
	ds_read2_b32 v[4:5], v13 offset0:186 offset1:251
	s_waitcnt lgkmcnt(0)
	v_cvt_pk_bf16_f32 v3, v4, v5
	ds_read2_b32 v[4:5], v14 offset0:60 offset1:125
	s_waitcnt lgkmcnt(0)
	v_cvt_pk_bf16_f32 v4, v4, v5
	ds_read2_b32 v[6:7], v14 offset0:190 offset1:255
	v_add_u32_e32 v14, s26, v44
	s_waitcnt lgkmcnt(0)
	v_cvt_pk_bf16_f32 v5, v6, v7
	v_mad_i64_i32 v[6:7], s[0:1], v14, s39, v[36:37]
	global_store_dwordx4 v[6:7], v[2:5], off
	s_waitcnt lgkmcnt(0)

; #define LAS __attribute__((address_space(3)))
; #define LDS_WAIT() asm volatile("s_waitcnt lgkmcnt(0)" ::: "memory")
; __device__ __forceinline__ void transpose_item(const float* __restrict__ W, int N, int src_n0, int n_valid, bf16_t* __restrict__ WT, int Kd, int dst_row0, int k0, ...
;     const int c4 = (lane & 15) * 4, kr = lane >> 4;
; #pragma unroll 4
;     for (int i = 0; i < 16; ++i) { const int kk = 4 * i + kr;
;         f32x4 v = {0.f, 0.f, 0.f, 0.f};
;         if (c4 < n_valid) v = *(const f32x4*)(W + (size_t)(k0 + kk) * N + src_n0 + c4);
;         LAS float* d = scr + kk * 65 + c4; d[0] = v.x; d[1] = v.y; d[2] = v.z; d[3] = v.w; }
;     LDS_WAIT();
;     const int c8 = lane & 7;
; #pragma unroll
;     for (int j = 0; j < 8; ++j) { const int n = (lane >> 3) + 8 * j; const LAS float* s = scr + (8 * c8) * 65 + n;
;         const float sc = (scale != nullptr && n < n_valid) ? scale[src_n0 + n] : 1.f;
;         float ks[8];
; #pragma unroll
;         for (int i = 0; i < 8; ++i) ks[i] = (kscale != nullptr) ? kscale[k0 + 8 * c8 + i] * sc : sc;
.LBB0_39:
	v_lshl_add_u64 v[152:153], v[36:37], 0, s[0:1]
	v_lshl_add_u64 v[156:157], v[6:7], 0, s[0:1]
	v_lshl_add_u64 v[160:161], v[4:5], 0, s[0:1]
	v_lshl_add_u64 v[164:165], v[2:3], 0, s[0:1]
	global_load_dwordx4 v[152:155], v[152:153], off
	s_nop 0
	global_load_dwordx4 v[156:159], v[156:157], off
	s_nop 0
	global_load_dwordx4 v[160:163], v[160:161], off
	s_nop 0
	global_load_dwordx4 v[164:167], v[164:165], off
	s_nop 0
	s_add_u32 s0, s0, 0xb0000
	s_addc_u32 s1, s1, 0
	v_lshl_add_u64 v[168:169], v[36:37], 0, s[0:1]
	v_lshl_add_u64 v[172:173], v[6:7], 0, s[0:1]
	v_lshl_add_u64 v[176:177], v[4:5], 0, s[0:1]
	v_lshl_add_u64 v[180:181], v[2:3], 0, s[0:1]
	global_load_dwordx4 v[168:171], v[168:169], off
	s_nop 0
	global_load_dwordx4 v[172:175], v[172:173], off
	s_nop 0
	global_load_dwordx4 v[176:179], v[176:177], off
	s_nop 0
	global_load_dwordx4 v[180:183], v[180:181], off
	s_nop 0
	s_add_u32 s0, s0, 0xb0000
	s_addc_u32 s1, s1, 0
	v_lshl_add_u64 v[184:185], v[36:37], 0, s[0:1]
	v_lshl_add_u64 v[188:189], v[6:7], 0, s[0:1]
	v_lshl_add_u64 v[192:193], v[4:5], 0, s[0:1]
	v_lshl_add_u64 v[196:197], v[2:3], 0, s[0:1]
	global_load_dwordx4 v[184:187], v[184:185], off
	s_nop 0
	global_load_dwordx4 v[188:191], v[188:189], off
	s_nop 0
	global_load_dwordx4 v[192:195], v[192:193], off
	s_nop 0
	global_load_dwordx4 v[196:199], v[196:197], off
	s_nop 0
	s_add_u32 s0, s0, 0xb0000
	s_addc_u32 s1, s1, 0
	v_lshl_add_u64 v[200:201], v[36:37], 0, s[0:1]
	v_lshl_add_u64 v[204:205], v[6:7], 0, s[0:1]
	v_lshl_add_u64 v[208:209], v[4:5], 0, s[0:1]
	v_lshl_add_u64 v[212:213], v[2:3], 0, s[0:1]
	global_load_dwordx4 v[200:203], v[200:201], off
	s_nop 0
	global_load_dwordx4 v[204:207], v[204:205], off
	s_nop 0
	global_load_dwordx4 v[208:211], v[208:209], off
	s_nop 0
	global_load_dwordx4 v[212:215], v[212:213], off
	s_nop 0
	s_add_u32 s0, s0, 0xb0000
	s_addc_u32 s1, s1, 0
	v_add_u32_e32 v74, 0x410, v14
	v_add_u32_e32 v75, 0x418, v14
	v_add_u32_e32 v76, 0x820, v14
	v_add_u32_e32 v77, 0x828, v14
	v_add_u32_e32 v78, 0xc30, v14
	v_add_u32_e32 v79, 0xc38, v14
	s_waitcnt vmcnt(15)
	ds_write2_b32 v14, v152, v153 offset1:1
	ds_write2_b32 v14, v154, v155 offset0:2 offset1:3
	s_waitcnt vmcnt(14)
	ds_write2_b32 v74, v156, v157 offset1:1
	ds_write2_b32 v75, v158, v159 offset1:1
	s_waitcnt vmcnt(13)
	ds_write2_b32 v76, v160, v161 offset1:1
	ds_write2_b32 v77, v162, v163 offset1:1
	s_waitcnt vmcnt(12)
	ds_write2_b32 v78, v164, v165 offset1:1
	ds_write2_b32 v79, v166, v167 offset1:1
	v_add_u32_e32 v14, 0x1040, v14
	v_add_u32_e32 v74, 0x410, v14
	v_add_u32_e32 v75, 0x418, v14
	v_add_u32_e32 v76, 0x820, v14
	v_add_u32_e32 v77, 0x828, v14
	v_add_u32_e32 v78, 0xc30, v14
	v_add_u32_e32 v79, 0xc38, v14
	s_waitcnt vmcnt(11)
	ds_write2_b32 v14, v168, v169 offset1:1
	ds_write2_b32 v14, v170, v171 offset0:2 offset1:3
	s_waitcnt vmcnt(10)
	ds_write2_b32 v74, v172, v173 offset1:1
	ds_write2_b32 v75, v174, v175 offset1:1
	s_waitcnt vmcnt(9)
	ds_write2_b32 v76, v176, v177 offset1:1
	ds_write2_b32 v77, v178, v179 offset1:1
	s_waitcnt vmcnt(8)
	ds_write2_b32 v78, v180, v181 offset1:1
	ds_write2_b32 v79, v182, v183 offset1:1
	v_add_u32_e32 v14, 0x1040, v14
	v_add_u32_e32 v74, 0x410, v14
	v_add_u32_e32 v75, 0x418, v14
	v_add_u32_e32 v76, 0x820, v14
	v_add_u32_e32 v77, 0x828, v14
	v_add_u32_e32 v78, 0xc30, v14
	v_add_u32_e32 v79, 0xc38, v14
	s_waitcnt vmcnt(7)
	ds_write2_b32 v14, v184, v185 offset1:1
	ds_write2_b32 v14, v186, v187 offset0:2 offset1:3
	s_waitcnt vmcnt(6)
	ds_write2_b32 v74, v188, v189 offset1:1
	ds_write2_b32 v75, v190, v191 offset1:1
	s_waitcnt vmcnt(5)
	ds_write2_b32 v76, v192, v193 offset1:1
	ds_write2_b32 v77, v194, v195 offset1:1
	s_waitcnt vmcnt(4)
	ds_write2_b32 v78, v196, v197 offset1:1
	ds_write2_b32 v79, v198, v199 offset1:1
	v_add_u32_e32 v14, 0x1040, v14
	v_add_u32_e32 v74, 0x410, v14
	v_add_u32_e32 v75, 0x418, v14
	v_add_u32_e32 v76, 0x820, v14
	v_add_u32_e32 v77, 0x828, v14
	v_add_u32_e32 v78, 0xc30, v14
	v_add_u32_e32 v79, 0xc38, v14
	s_waitcnt vmcnt(3)
	ds_write2_b32 v14, v200, v201 offset1:1
	ds_write2_b32 v14, v202, v203 offset0:2 offset1:3
	s_waitcnt vmcnt(2)
	ds_write2_b32 v74, v204, v205 offset1:1
	ds_write2_b32 v75, v206, v207 offset1:1
	s_waitcnt vmcnt(1)
	ds_write2_b32 v76, v208, v209 offset1:1
	ds_write2_b32 v77, v210, v211 offset1:1
	s_waitcnt vmcnt(0)
	ds_write2_b32 v78, v212, v213 offset1:1
	ds_write2_b32 v79, v214, v215 offset1:1
	v_add_u32_e32 v14, 0x1040, v14
	s_waitcnt lgkmcnt(0)
	v_or_b32_e32 v3, s27, v12
	v_mov_b32_e32 v2, 1.0
	s_and_b64 vcc, exec, s[24:25]
	v_lshlrev_b32_e32 v4, 2, v3
	v_mov_b32_e32 v3, 1.0
	v_mov_b32_e32 v200, 1.0
	v_mov_b32_e32 v201, 1.0
	v_mov_b32_e32 v202, 1.0
	v_mov_b32_e32 v203, 1.0
	v_mov_b32_e32 v204, 1.0
	v_mov_b32_e32 v205, 1.0
	v_mov_b32_e32 v206, 1.0
	v_mov_b32_e32 v207, 1.0
	s_cbranch_vccz .Lks_hoist_done
	global_load_dword v200, v4, s[64:65]
	global_load_dword v201, v4, s[64:65] offset:4
	global_load_dword v202, v4, s[64:65] offset:8
	global_load_dword v203, v4, s[64:65] offset:12
	global_load_dword v204, v4, s[64:65] offset:16
	global_load_dword v205, v4, s[64:65] offset:20
	global_load_dword v206, v4, s[64:65] offset:24
	global_load_dword v207, v4, s[64:65] offset:28
.Lks_hoist_done:
	s_cbranch_vccz .LBB0_42
.LBB0_42:
	v_cndmask_b32_e64 v5, 0, 1, s[24:25]
	v_cmp_ne_u32_e64 s[0:1], 1, v5
	s_andn2_b64 vcc, exec, s[24:25]
	s_cbranch_vccnz .LBB0_44
.LBB0_44:
	v_mov_b32_e32 v6, 1.0
	s_and_b64 vcc, exec, s[0:1]
	v_mov_b32_e32 v36, 1.0
	s_cbranch_vccnz .LBB0_46
.LBB0_46:
	s_and_b64 vcc, exec, s[0:1]
	s_cbranch_vccnz .LBB0_48
.LBB0_48:
	v_mov_b32_e32 v7, 1.0
	s_and_b64 vcc, exec, s[0:1]
	v_mov_b32_e32 v14, 1.0
	s_cbranch_vccnz .LBB0_50
; __device__ __forceinline__ unsigned cvt_pk_bf16(float lo, float hi) { unsigned r; asm volatile("v_cvt_pk_bf16_f32 %0, %1, %2" : "=v"(r) : "v"(lo), "v"(hi)); return r; }
; #define LAS __attribute__((address_space(3)))
; __device__ __forceinline__ void transpose_item(const float* __restrict__ W, int N, int src_n0, int n_valid, bf16_t* __restrict__ WT, int Kd, int dst_row0, int k0, ...
;     ...
;     for (int j = 0; j < 8; ++j) { const int n = (lane >> 3) + 8 * j; const LAS float* s = scr + (8 * c8) * 65 + n;
;         const float sc = (scale != nullptr && n < n_valid) ? scale[src_n0 + n] : 1.f;
;         float ks[8];
; #pragma unroll
;         for (int i = 0; i < 8; ++i) ks[i] = (kscale != nullptr) ? kscale[k0 + 8 * c8 + i] * sc : sc;
;         u32x4 o; o.x = cvt_pk_bf16(s[0 * 65] * ks[0], s[1 * 65] * ks[1]); o.y = cvt_pk_bf16(s[2 * 65] * ks[2], s[3 * 65] * ks[3]); o.z = cvt_pk_bf16(s[4 * 65] * ks[4], s[5 * 65] * ks[5]); o.w = cvt_pk_bf16(s[6 * 65] * ks[6], s[7 * 65] * ks[7]);
;         *(u32x4*)(WT + (size_t)(dst_row0 + n) * Kd + k0 + 8 * c8) = o; }
.LBB0_50:
	s_and_b64 vcc, exec, s[0:1]
	s_cbranch_vccnz .LBB0_52
.LBB0_52:
	v_mov_b32_e32 v37, 1.0
	s_and_b64 vcc, exec, s[0:1]
	v_mov_b32_e32 v58, 1.0
	s_cbranch_vccnz .LBB0_54
.LBB0_54:
	s_and_b64 vcc, exec, s[0:1]
	s_cbranch_vccnz .LBB0_56
.LBB0_56:
	ds_read2_b32 v[60:61], v13 offset1:65
	v_add_u32_e32 v5, 0x400, v13
	v_add_u32_e32 v64, s26, v8
	s_lshl_b32 s6, s27, 1
	v_ashrrev_i32_e32 v65, 31, v64
	s_waitcnt vmcnt(0) lgkmcnt(0)
	v_mul_f32_e32 v3, v200, v60
	v_mul_f32_e32 v2, v201, v61
	v_cvt_pk_bf16_f32 v60, v3, v2
	ds_read2_b32 v[2:3], v13 offset0:130 offset1:195
	v_lshlrev_b64 v[64:65], 12, v[64:65]
	s_and_b64 vcc, exec, s[0:1]
	s_waitcnt lgkmcnt(0)
	v_mul_f32_e32 v2, v202, v2
	v_mul_f32_e32 v3, v203, v3
	v_cvt_pk_bf16_f32 v61, v2, v3
	ds_read2_b32 v[2:3], v5 offset0:4 offset1:69
	v_mov_b32_e32 v6, 1.0
	s_waitcnt lgkmcnt(0)
	v_mul_f32_e32 v2, v204, v2
	v_mul_f32_e32 v3, v205, v3
	v_cvt_pk_bf16_f32 v62, v2, v3
	ds_read2_b32 v[66:67], v5 offset0:134 offset1:199
	v_lshl_add_u64 v[2:3], v[18:19], 0, s[6:7]
	v_lshl_add_u64 v[64:65], v[2:3], 0, v[64:65]
	s_waitcnt lgkmcnt(0)
	v_mul_f32_e32 v7, v206, v66
	v_mul_f32_e32 v14, v207, v67
	v_cvt_pk_bf16_f32 v63, v7, v14
	v_mov_b32_e32 v7, 1.0
	global_store_dwordx4 v[64:65], v[60:63], off
	s_cbranch_vccnz .LBB0_58
.LBB0_58:
	s_and_b64 vcc, exec, s[0:1]
	s_cbranch_vccnz .LBB0_60
.LBB0_60:
	v_mov_b32_e32 v37, 1.0
	s_and_b64 vcc, exec, s[0:1]
	v_mov_b32_e32 v58, 1.0
	s_cbranch_vccnz .LBB0_62
.LBB0_62:
	s_and_b64 vcc, exec, s[0:1]
	s_cbranch_vccnz .LBB0_64
.LBB0_64:
	v_mov_b32_e32 v14, 1.0
	s_and_b64 vcc, exec, s[0:1]
	v_mov_b32_e32 v36, 1.0
	s_cbranch_vccnz .LBB0_66
.LBB0_66:
	s_and_b64 vcc, exec, s[0:1]
	s_cbranch_vccnz .LBB0_68
.LBB0_68:
	v_mov_b32_e32 v59, 1.0
	s_and_b64 vcc, exec, s[0:1]
	v_mov_b32_e32 v60, 1.0
	s_cbranch_vccnz .LBB0_70
.LBB0_70:
	s_and_b64 vcc, exec, s[0:1]
	s_cbranch_vccnz .LBB0_72
.LBB0_72:
	ds_read2_b32 v[62:63], v13 offset0:8 offset1:73
	v_add_u32_e32 v66, s26, v38
	v_ashrrev_i32_e32 v67, 31, v66
	v_lshlrev_b64 v[66:67], 12, v[66:67]
	s_and_b64 vcc, exec, s[0:1]
	s_waitcnt lgkmcnt(0)
	v_mul_f32_e32 v7, v200, v62
	v_mul_f32_e32 v6, v201, v63
	v_cvt_pk_bf16_f32 v62, v7, v6
	ds_read2_b32 v[6:7], v13 offset0:138 offset1:203
	v_lshl_add_u64 v[66:67], v[2:3], 0, v[66:67]
	s_waitcnt lgkmcnt(0)
	v_mul_f32_e32 v6, v202, v6
	v_mul_f32_e32 v7, v203, v7
	v_cvt_pk_bf16_f32 v63, v6, v7
	ds_read2_b32 v[64:65], v5 offset0:12 offset1:77
	v_mov_b32_e32 v6, 1.0
	s_waitcnt lgkmcnt(0)
	v_mul_f32_e32 v7, v204, v64
	v_mul_f32_e32 v14, v205, v65
	v_cvt_pk_bf16_f32 v64, v7, v14
	ds_read2_b32 v[36:37], v5 offset0:142 offset1:207
	s_waitcnt lgkmcnt(0)
	v_mul_f32_e32 v7, v206, v36
	v_mul_f32_e32 v14, v207, v37
	v_cvt_pk_bf16_f32 v65, v7, v14
	v_mov_b32_e32 v7, 1.0
	global_store_dwordx4 v[66:67], v[62:65], off
	s_cbranch_vccnz .LBB0_74
.LBB0_74:
	s_and_b64 vcc, exec, s[0:1]
	s_cbranch_vccnz .LBB0_76
.LBB0_76:
	v_mov_b32_e32 v37, 1.0
	s_and_b64 vcc, exec, s[0:1]
	v_mov_b32_e32 v58, 1.0
	s_cbranch_vccnz .LBB0_78
.LBB0_78:
	s_and_b64 vcc, exec, s[0:1]
	s_cbranch_vccnz .LBB0_80
.LBB0_80:
	v_mov_b32_e32 v14, 1.0
	s_and_b64 vcc, exec, s[0:1]
	v_mov_b32_e32 v36, 1.0
	s_cbranch_vccnz .LBB0_82
.LBB0_82:
	s_and_b64 vcc, exec, s[0:1]
	s_cbranch_vccnz .LBB0_84
.LBB0_84:
	v_mov_b32_e32 v59, 1.0
	s_and_b64 vcc, exec, s[0:1]
	v_mov_b32_e32 v60, 1.0
	s_cbranch_vccnz .LBB0_86
.LBB0_86:
	s_and_b64 vcc, exec, s[0:1]
	s_cbranch_vccnz .LBB0_88
.LBB0_88:
	ds_read2_b32 v[62:63], v13 offset0:16 offset1:81
	v_add_u32_e32 v66, s26, v39
	v_ashrrev_i32_e32 v67, 31, v66
	v_lshlrev_b64 v[66:67], 12, v[66:67]
	s_and_b64 vcc, exec, s[0:1]
	s_waitcnt lgkmcnt(0)
	v_mul_f32_e32 v7, v200, v62
	v_mul_f32_e32 v6, v201, v63
	v_cvt_pk_bf16_f32 v62, v7, v6
	ds_read2_b32 v[6:7], v13 offset0:146 offset1:211
	v_lshl_add_u64 v[66:67], v[2:3], 0, v[66:67]
	s_waitcnt lgkmcnt(0)
	v_mul_f32_e32 v6, v202, v6
	v_mul_f32_e32 v7, v203, v7
	v_cvt_pk_bf16_f32 v63, v6, v7
	ds_read2_b32 v[64:65], v5 offset0:20 offset1:85
	v_mov_b32_e32 v6, 1.0
	s_waitcnt lgkmcnt(0)
	v_mul_f32_e32 v7, v204, v64
	v_mul_f32_e32 v14, v205, v65
	v_cvt_pk_bf16_f32 v64, v7, v14
	ds_read2_b32 v[36:37], v5 offset0:150 offset1:215
	s_waitcnt lgkmcnt(0)
	v_mul_f32_e32 v7, v206, v36
	v_mul_f32_e32 v14, v207, v37
	v_cvt_pk_bf16_f32 v65, v7, v14
	v_mov_b32_e32 v7, 1.0
	global_store_dwordx4 v[66:67], v[62:65], off
	s_cbranch_vccnz .LBB0_90
.LBB0_90:
	s_and_b64 vcc, exec, s[0:1]
	s_cbranch_vccnz .LBB0_92
.LBB0_92:
	v_mov_b32_e32 v37, 1.0
	s_and_b64 vcc, exec, s[0:1]
	v_mov_b32_e32 v58, 1.0
	s_cbranch_vccnz .LBB0_94
.LBB0_94:
	s_and_b64 vcc, exec, s[0:1]
	s_cbranch_vccnz .LBB0_96
.LBB0_96:
	v_mov_b32_e32 v14, 1.0
	s_and_b64 vcc, exec, s[0:1]
	v_mov_b32_e32 v36, 1.0
	s_cbranch_vccnz .LBB0_98
.LBB0_98:
	s_and_b64 vcc, exec, s[0:1]
	s_cbranch_vccnz .LBB0_100
.LBB0_100:
	v_mov_b32_e32 v59, 1.0
	s_and_b64 vcc, exec, s[0:1]
	v_mov_b32_e32 v60, 1.0
	s_cbranch_vccnz .LBB0_102
.LBB0_102:
	s_and_b64 vcc, exec, s[0:1]
	s_cbranch_vccnz .LBB0_104
.LBB0_104:
	ds_read2_b32 v[62:63], v13 offset0:24 offset1:89
	v_add_u32_e32 v66, s26, v40
	v_ashrrev_i32_e32 v67, 31, v66
	v_lshlrev_b64 v[66:67], 12, v[66:67]
	s_and_b64 vcc, exec, s[0:1]
	s_waitcnt lgkmcnt(0)
	v_mul_f32_e32 v7, v200, v62
	v_mul_f32_e32 v6, v201, v63
	v_cvt_pk_bf16_f32 v62, v7, v6
	ds_read2_b32 v[6:7], v13 offset0:154 offset1:219
	v_lshl_add_u64 v[66:67], v[2:3], 0, v[66:67]
	s_waitcnt lgkmcnt(0)
	v_mul_f32_e32 v6, v202, v6
	v_mul_f32_e32 v7, v203, v7
	v_cvt_pk_bf16_f32 v63, v6, v7
	ds_read2_b32 v[64:65], v5 offset0:28 offset1:93
	v_mov_b32_e32 v6, 1.0
	s_waitcnt lgkmcnt(0)
	v_mul_f32_e32 v7, v204, v64
	v_mul_f32_e32 v14, v205, v65
	v_cvt_pk_bf16_f32 v64, v7, v14
	ds_read2_b32 v[36:37], v5 offset0:158 offset1:223
	s_waitcnt lgkmcnt(0)
	v_mul_f32_e32 v7, v206, v36
	v_mul_f32_e32 v14, v207, v37
	v_cvt_pk_bf16_f32 v65, v7, v14
	v_mov_b32_e32 v7, 1.0
	global_store_dwordx4 v[66:67], v[62:65], off
	s_cbranch_vccnz .LBB0_106
; __device__ __forceinline__ unsigned cvt_pk_bf16(float lo, float hi) { unsigned r; asm volatile("v_cvt_pk_bf16_f32 %0, %1, %2" : "=v"(r) : "v"(lo), "v"(hi)); return r; }
; #define LAS __attribute__((address_space(3)))
; #define LDS_WAIT() asm volatile("s_waitcnt lgkmcnt(0)" ::: "memory")
; __device__ __forceinline__ void transpose_item(const float* __restrict__ W, int N, int src_n0, int n_valid, bf16_t* __restrict__ WT, int Kd, int dst_row0, int k0, ...
;     ...
;     for (int j = 0; j < 8; ++j) { const int n = (lane >> 3) + 8 * j; const LAS float* s = scr + (8 * c8) * 65 + n;
;         const float sc = (scale != nullptr && n < n_valid) ? scale[src_n0 + n] : 1.f;
;         float ks[8];
; #pragma unroll
;         for (int i = 0; i < 8; ++i) ks[i] = (kscale != nullptr) ? kscale[k0 + 8 * c8 + i] * sc : sc;
;         u32x4 o; o.x = cvt_pk_bf16(s[0 * 65] * ks[0], s[1 * 65] * ks[1]); o.y = cvt_pk_bf16(s[2 * 65] * ks[2], s[3 * 65] * ks[3]); o.z = cvt_pk_bf16(s[4 * 65] * ks[4], s[5 * 65] * ks[5]); o.w = cvt_pk_bf16(s[6 * 65] * ks[6], s[7 * 65] * ks[7]);
;         *(u32x4*)(WT + (size_t)(dst_row0 + n) * Kd + k0 + 8 * c8) = o; }
;     LDS_WAIT();
.LBB0_106:
	s_and_b64 vcc, exec, s[0:1]
	s_cbranch_vccnz .LBB0_108
.LBB0_108:
	v_mov_b32_e32 v37, 1.0
	s_and_b64 vcc, exec, s[0:1]
	v_mov_b32_e32 v58, 1.0
	s_cbranch_vccnz .LBB0_110
.LBB0_110:
	s_and_b64 vcc, exec, s[0:1]
	s_cbranch_vccnz .LBB0_112
.LBB0_112:
	v_mov_b32_e32 v14, 1.0
	s_and_b64 vcc, exec, s[0:1]
	v_mov_b32_e32 v36, 1.0
	s_cbranch_vccnz .LBB0_114
.LBB0_114:
	s_and_b64 vcc, exec, s[0:1]
	s_cbranch_vccnz .LBB0_116
.LBB0_116:
	v_mov_b32_e32 v59, 1.0
	s_and_b64 vcc, exec, s[0:1]
	v_mov_b32_e32 v60, 1.0
	s_cbranch_vccnz .LBB0_118
.LBB0_118:
	s_and_b64 vcc, exec, s[0:1]
	s_cbranch_vccnz .LBB0_120
.LBB0_120:
	ds_read2_b32 v[62:63], v13 offset0:32 offset1:97
	v_add_u32_e32 v66, s26, v41
	v_ashrrev_i32_e32 v67, 31, v66
	v_lshlrev_b64 v[66:67], 12, v[66:67]
	s_and_b64 vcc, exec, s[0:1]
	s_waitcnt lgkmcnt(0)
	v_mul_f32_e32 v7, v200, v62
	v_mul_f32_e32 v6, v201, v63
	v_cvt_pk_bf16_f32 v62, v7, v6
	ds_read2_b32 v[6:7], v13 offset0:162 offset1:227
	v_lshl_add_u64 v[66:67], v[2:3], 0, v[66:67]
	s_waitcnt lgkmcnt(0)
	v_mul_f32_e32 v6, v202, v6
	v_mul_f32_e32 v7, v203, v7
	v_cvt_pk_bf16_f32 v63, v6, v7
	ds_read2_b32 v[64:65], v5 offset0:36 offset1:101
	v_mov_b32_e32 v6, 1.0
	s_waitcnt lgkmcnt(0)
	v_mul_f32_e32 v7, v204, v64
	v_mul_f32_e32 v14, v205, v65
	v_cvt_pk_bf16_f32 v64, v7, v14
	ds_read2_b32 v[36:37], v5 offset0:166 offset1:231
	s_waitcnt lgkmcnt(0)
	v_mul_f32_e32 v7, v206, v36
	v_mul_f32_e32 v14, v207, v37
	v_cvt_pk_bf16_f32 v65, v7, v14
	v_mov_b32_e32 v7, 1.0
	global_store_dwordx4 v[66:67], v[62:65], off
	s_cbranch_vccnz .LBB0_122
.LBB0_122:
	s_and_b64 vcc, exec, s[0:1]
	s_cbranch_vccnz .LBB0_124
.LBB0_124:
	v_mov_b32_e32 v37, 1.0
	s_and_b64 vcc, exec, s[0:1]
	v_mov_b32_e32 v58, 1.0
	s_cbranch_vccnz .LBB0_126
.LBB0_126:
	s_and_b64 vcc, exec, s[0:1]
	s_cbranch_vccnz .LBB0_128
.LBB0_128:
	v_mov_b32_e32 v14, 1.0
	s_and_b64 vcc, exec, s[0:1]
	v_mov_b32_e32 v36, 1.0
	s_cbranch_vccnz .LBB0_130
.LBB0_130:
	s_and_b64 vcc, exec, s[0:1]
	s_cbranch_vccnz .LBB0_132
.LBB0_132:
	v_mov_b32_e32 v59, 1.0
	s_and_b64 vcc, exec, s[0:1]
	v_mov_b32_e32 v60, 1.0
	s_cbranch_vccnz .LBB0_134
.LBB0_134:
	s_and_b64 vcc, exec, s[0:1]
	s_cbranch_vccnz .LBB0_136
.LBB0_136:
	ds_read2_b32 v[62:63], v13 offset0:40 offset1:105
	v_add_u32_e32 v66, s26, v42
	v_ashrrev_i32_e32 v67, 31, v66
	v_lshlrev_b64 v[66:67], 12, v[66:67]
	s_and_b64 vcc, exec, s[0:1]
	s_waitcnt lgkmcnt(0)
	v_mul_f32_e32 v7, v200, v62
	v_mul_f32_e32 v6, v201, v63
	v_cvt_pk_bf16_f32 v62, v7, v6
	ds_read2_b32 v[6:7], v13 offset0:170 offset1:235
	v_lshl_add_u64 v[66:67], v[2:3], 0, v[66:67]
	s_waitcnt lgkmcnt(0)
	v_mul_f32_e32 v6, v202, v6
	v_mul_f32_e32 v7, v203, v7
	v_cvt_pk_bf16_f32 v63, v6, v7
	ds_read2_b32 v[64:65], v5 offset0:44 offset1:109
	v_mov_b32_e32 v6, 1.0
	s_waitcnt lgkmcnt(0)
	v_mul_f32_e32 v7, v204, v64
	v_mul_f32_e32 v14, v205, v65
	v_cvt_pk_bf16_f32 v64, v7, v14
	ds_read2_b32 v[36:37], v5 offset0:174 offset1:239
	s_waitcnt lgkmcnt(0)
	v_mul_f32_e32 v7, v206, v36
	v_mul_f32_e32 v14, v207, v37
	v_cvt_pk_bf16_f32 v65, v7, v14
	v_mov_b32_e32 v7, 1.0
	global_store_dwordx4 v[66:67], v[62:65], off
	s_cbranch_vccnz .LBB0_138
.LBB0_138:
	s_and_b64 vcc, exec, s[0:1]
	s_cbranch_vccnz .LBB0_140
.LBB0_140:
	v_mov_b32_e32 v37, 1.0
	s_and_b64 vcc, exec, s[0:1]
	v_mov_b32_e32 v58, 1.0
	s_cbranch_vccnz .LBB0_142
.LBB0_142:
	s_and_b64 vcc, exec, s[0:1]
	s_cbranch_vccnz .LBB0_144
.LBB0_144:
	v_mov_b32_e32 v14, 1.0
	s_and_b64 vcc, exec, s[0:1]
	v_mov_b32_e32 v36, 1.0
	s_cbranch_vccnz .LBB0_146
.LBB0_146:
	s_and_b64 vcc, exec, s[0:1]
	s_cbranch_vccnz .LBB0_148
.LBB0_148:
	v_mov_b32_e32 v59, 1.0
	s_and_b64 vcc, exec, s[0:1]
	v_mov_b32_e32 v60, 1.0
	s_cbranch_vccnz .LBB0_150
.LBB0_150:
	s_and_b64 vcc, exec, s[0:1]
	s_cbranch_vccnz .LBB0_152
.LBB0_152:
	ds_read2_b32 v[62:63], v13 offset0:48 offset1:113
	v_add_u32_e32 v66, s26, v43
	v_ashrrev_i32_e32 v67, 31, v66
	v_lshlrev_b64 v[66:67], 12, v[66:67]
	s_and_b64 vcc, exec, s[0:1]
	s_waitcnt lgkmcnt(0)
	v_mul_f32_e32 v7, v200, v62
	v_mul_f32_e32 v6, v201, v63
	v_cvt_pk_bf16_f32 v62, v7, v6
	ds_read2_b32 v[6:7], v13 offset0:178 offset1:243
	v_lshl_add_u64 v[66:67], v[2:3], 0, v[66:67]
	s_waitcnt lgkmcnt(0)
	v_mul_f32_e32 v6, v202, v6
	v_mul_f32_e32 v7, v203, v7
	v_cvt_pk_bf16_f32 v63, v6, v7
	ds_read2_b32 v[64:65], v5 offset0:52 offset1:117
	v_mov_b32_e32 v6, 1.0
	s_waitcnt lgkmcnt(0)
	v_mul_f32_e32 v7, v204, v64
	v_mul_f32_e32 v14, v205, v65
	v_cvt_pk_bf16_f32 v64, v7, v14
	ds_read2_b32 v[36:37], v5 offset0:182 offset1:247
	s_waitcnt lgkmcnt(0)
	v_mul_f32_e32 v7, v206, v36
	v_mul_f32_e32 v14, v207, v37
	v_cvt_pk_bf16_f32 v65, v7, v14
	v_mov_b32_e32 v7, 1.0
	global_store_dwordx4 v[66:67], v[62:65], off
	s_cbranch_vccnz .LBB0_154
.LBB0_154:
	s_and_b64 vcc, exec, s[0:1]
	s_cbranch_vccnz .LBB0_156
.LBB0_156:
	v_mov_b32_e32 v14, 1.0
	s_and_b64 vcc, exec, s[0:1]
	v_mov_b32_e32 v36, 1.0
	s_cbranch_vccnz .LBB0_158
.LBB0_158:
	s_and_b64 vcc, exec, s[0:1]
	s_cbranch_vccnz .LBB0_160
.LBB0_160:
	v_mov_b32_e32 v37, 1.0
	s_and_b64 vcc, exec, s[0:1]
	v_mov_b32_e32 v59, 1.0
	s_cbranch_vccnz .LBB0_162
.LBB0_162:
	s_and_b64 vcc, exec, s[0:1]
	s_cbranch_vccnz .LBB0_164
.LBB0_164:
	v_mov_b32_e32 v58, 1.0
	s_and_b64 vcc, exec, s[0:1]
	v_mov_b32_e32 v60, 1.0
	s_cbranch_vccnz .LBB0_166
.LBB0_166:
	s_and_b64 vcc, exec, s[0:1]
	s_cbranch_vccnz .LBB0_168
.LBB0_168:
	ds_read2_b32 v[62:63], v13 offset0:56 offset1:121
	s_waitcnt lgkmcnt(0)
	v_mul_f32_e32 v6, v201, v63
	v_mul_f32_e32 v4, v200, v62
	v_cvt_pk_bf16_f32 v62, v4, v6
	ds_read2_b32 v[6:7], v13 offset0:186 offset1:251
	s_waitcnt lgkmcnt(0)
	v_mul_f32_e32 v4, v202, v6
	v_mul_f32_e32 v6, v203, v7
	v_cvt_pk_bf16_f32 v63, v4, v6
	ds_read2_b32 v[6:7], v5 offset0:60 offset1:125
	s_waitcnt lgkmcnt(0)
	v_mul_f32_e32 v4, v204, v6
	v_mul_f32_e32 v6, v205, v7
	v_cvt_pk_bf16_f32 v64, v4, v6
	ds_read2_b32 v[4:5], v5 offset0:190 offset1:255
	v_add_u32_e32 v6, s26, v44
	v_ashrrev_i32_e32 v7, 31, v6
	v_lshlrev_b64 v[6:7], 12, v[6:7]
	v_lshl_add_u64 v[2:3], v[2:3], 0, v[6:7]
	s_waitcnt lgkmcnt(0)
	v_mul_f32_e32 v4, v206, v4
	v_mul_f32_e32 v5, v207, v5
	v_cvt_pk_bf16_f32 v65, v4, v5
	global_store_dwordx4 v[2:3], v[62:65], off
	s_waitcnt lgkmcnt(0)

; __device__ __forceinline__ unsigned cvt_pk_bf16(float lo, float hi) { unsigned r; asm volatile("v_cvt_pk_bf16_f32 %0, %1, %2" : "=v"(r) : "v"(lo), "v"(hi)); return r; }
; #define LAS __attribute__((address_space(3)))
; #define LDS_WAIT() asm volatile("s_waitcnt lgkmcnt(0)" ::: "memory")
; __device__ __forceinline__ void transpose_item(const float* __restrict__ W, int N, int src_n0, int n_valid, bf16_t* __restrict__ WT, int Kd, int dst_row0, int k0, ...
;     const int c4 = (lane & 15) * 4, kr = lane >> 4;
; #pragma unroll 4
;     for (int i = 0; i < 16; ++i) { const int kk = 4 * i + kr;
;         f32x4 v = {0.f, 0.f, 0.f, 0.f};
;         if (c4 < n_valid) v = *(const f32x4*)(W + (size_t)(k0 + kk) * N + src_n0 + c4);
;         LAS float* d = scr + kk * 65 + c4; d[0] = v.x; d[1] = v.y; d[2] = v.z; d[3] = v.w; }
;     LDS_WAIT();
;     const int c8 = lane & 7;
; #pragma unroll
;     for (int j = 0; j < 8; ++j) { const int n = (lane >> 3) + 8 * j; const LAS float* s = scr + (8 * c8) * 65 + n;
;         const float sc = (scale != nullptr && n < n_valid) ? scale[src_n0 + n] : 1.f;
;         float ks[8];
; #pragma unroll
;         for (int i = 0; i < 8; ++i) ks[i] = (kscale != nullptr) ? kscale[k0 + 8 * c8 + i] * sc : sc;
;         u32x4 o; o.x = cvt_pk_bf16(s[0 * 65] * ks[0], s[1 * 65] * ks[1]); o.y = cvt_pk_bf16(s[2 * 65] * ks[2], s[3 * 65] * ks[3]); o.z = cvt_pk_bf16(s[4 * 65] * ks[4], s[5 * 65] * ks[5]); o.w = cvt_pk_bf16(s[6 * 65] * ks[6], s[7 * 65] * ks[7]);
;         *(u32x4*)(WT + (size_t)(dst_row0 + n) * Kd + k0 + 8 * c8) = o; }
.LBB0_172:
	v_lshl_add_u64 v[152:153], v[36:37], 0, s[0:1]
	v_lshl_add_u64 v[156:157], v[6:7], 0, s[0:1]
	v_lshl_add_u64 v[160:161], v[4:5], 0, s[0:1]
	v_lshl_add_u64 v[164:165], v[2:3], 0, s[0:1]
	global_load_dwordx4 v[152:155], v[152:153], off
	s_nop 0
	global_load_dwordx4 v[156:159], v[156:157], off
	s_nop 0
	global_load_dwordx4 v[160:163], v[160:161], off
	s_nop 0
	global_load_dwordx4 v[164:167], v[164:165], off
	s_nop 0
	s_add_u32 s0, s0, 0x20000
	s_addc_u32 s1, s1, 0
	v_lshl_add_u64 v[168:169], v[36:37], 0, s[0:1]
	v_lshl_add_u64 v[172:173], v[6:7], 0, s[0:1]
	v_lshl_add_u64 v[176:177], v[4:5], 0, s[0:1]
	v_lshl_add_u64 v[180:181], v[2:3], 0, s[0:1]
	global_load_dwordx4 v[168:171], v[168:169], off
	s_nop 0
	global_load_dwordx4 v[172:175], v[172:173], off
	s_nop 0
	global_load_dwordx4 v[176:179], v[176:177], off
	s_nop 0
	global_load_dwordx4 v[180:183], v[180:181], off
	s_nop 0
	s_add_u32 s0, s0, 0x20000
	s_addc_u32 s1, s1, 0
	v_lshl_add_u64 v[184:185], v[36:37], 0, s[0:1]
	v_lshl_add_u64 v[188:189], v[6:7], 0, s[0:1]
	v_lshl_add_u64 v[192:193], v[4:5], 0, s[0:1]
	v_lshl_add_u64 v[196:197], v[2:3], 0, s[0:1]
	global_load_dwordx4 v[184:187], v[184:185], off
	s_nop 0
	global_load_dwordx4 v[188:191], v[188:189], off
	s_nop 0
	global_load_dwordx4 v[192:195], v[192:193], off
	s_nop 0
	global_load_dwordx4 v[196:199], v[196:197], off
	s_nop 0
	s_add_u32 s0, s0, 0x20000
	s_addc_u32 s1, s1, 0
	v_lshl_add_u64 v[200:201], v[36:37], 0, s[0:1]
	v_lshl_add_u64 v[204:205], v[6:7], 0, s[0:1]
	v_lshl_add_u64 v[208:209], v[4:5], 0, s[0:1]
	v_lshl_add_u64 v[212:213], v[2:3], 0, s[0:1]
	global_load_dwordx4 v[200:203], v[200:201], off
	s_nop 0
	global_load_dwordx4 v[204:207], v[204:205], off
	s_nop 0
	global_load_dwordx4 v[208:211], v[208:209], off
	s_nop 0
	global_load_dwordx4 v[212:215], v[212:213], off
	s_nop 0
	s_add_u32 s0, s0, 0x20000
	s_addc_u32 s1, s1, 0
	v_add_u32_e32 v74, 0x410, v14
	v_add_u32_e32 v75, 0x418, v14
	v_add_u32_e32 v76, 0x820, v14
	v_add_u32_e32 v77, 0x828, v14
	v_add_u32_e32 v78, 0xc30, v14
	v_add_u32_e32 v79, 0xc38, v14
	s_waitcnt vmcnt(15)
	ds_write2_b32 v14, v152, v153 offset1:1
	ds_write2_b32 v14, v154, v155 offset0:2 offset1:3
	s_waitcnt vmcnt(14)
	ds_write2_b32 v74, v156, v157 offset1:1
	ds_write2_b32 v75, v158, v159 offset1:1
	s_waitcnt vmcnt(13)
	ds_write2_b32 v76, v160, v161 offset1:1
	ds_write2_b32 v77, v162, v163 offset1:1
	s_waitcnt vmcnt(12)
	ds_write2_b32 v78, v164, v165 offset1:1
	ds_write2_b32 v79, v166, v167 offset1:1
	v_add_u32_e32 v14, 0x1040, v14
	v_add_u32_e32 v74, 0x410, v14
	v_add_u32_e32 v75, 0x418, v14
	v_add_u32_e32 v76, 0x820, v14
	v_add_u32_e32 v77, 0x828, v14
	v_add_u32_e32 v78, 0xc30, v14
	v_add_u32_e32 v79, 0xc38, v14
	s_waitcnt vmcnt(11)
	ds_write2_b32 v14, v168, v169 offset1:1
	ds_write2_b32 v14, v170, v171 offset0:2 offset1:3
	s_waitcnt vmcnt(10)
	ds_write2_b32 v74, v172, v173 offset1:1
	ds_write2_b32 v75, v174, v175 offset1:1
	s_waitcnt vmcnt(9)
	ds_write2_b32 v76, v176, v177 offset1:1
	ds_write2_b32 v77, v178, v179 offset1:1
	s_waitcnt vmcnt(8)
	ds_write2_b32 v78, v180, v181 offset1:1
	ds_write2_b32 v79, v182, v183 offset1:1
	v_add_u32_e32 v14, 0x1040, v14
	v_add_u32_e32 v74, 0x410, v14
	v_add_u32_e32 v75, 0x418, v14
	v_add_u32_e32 v76, 0x820, v14
	v_add_u32_e32 v77, 0x828, v14
	v_add_u32_e32 v78, 0xc30, v14
	v_add_u32_e32 v79, 0xc38, v14
	s_waitcnt vmcnt(7)
	ds_write2_b32 v14, v184, v185 offset1:1
	ds_write2_b32 v14, v186, v187 offset0:2 offset1:3
	s_waitcnt vmcnt(6)
	ds_write2_b32 v74, v188, v189 offset1:1
	ds_write2_b32 v75, v190, v191 offset1:1
	s_waitcnt vmcnt(5)
	ds_write2_b32 v76, v192, v193 offset1:1
	ds_write2_b32 v77, v194, v195 offset1:1
	s_waitcnt vmcnt(4)
	ds_write2_b32 v78, v196, v197 offset1:1
	ds_write2_b32 v79, v198, v199 offset1:1
	v_add_u32_e32 v14, 0x1040, v14
	v_add_u32_e32 v74, 0x410, v14
	v_add_u32_e32 v75, 0x418, v14
	v_add_u32_e32 v76, 0x820, v14
	v_add_u32_e32 v77, 0x828, v14
	v_add_u32_e32 v78, 0xc30, v14
	v_add_u32_e32 v79, 0xc38, v14
	s_waitcnt vmcnt(3)
	ds_write2_b32 v14, v200, v201 offset1:1
	ds_write2_b32 v14, v202, v203 offset0:2 offset1:3
	s_waitcnt vmcnt(2)
	ds_write2_b32 v74, v204, v205 offset1:1
	ds_write2_b32 v75, v206, v207 offset1:1
	s_waitcnt vmcnt(1)
	ds_write2_b32 v76, v208, v209 offset1:1
	ds_write2_b32 v77, v210, v211 offset1:1
	s_waitcnt vmcnt(0)
	ds_write2_b32 v78, v212, v213 offset1:1
	ds_write2_b32 v79, v214, v215 offset1:1
	v_add_u32_e32 v14, 0x1040, v14
	s_lshl_b32 s0, s45, 6
	s_lshl_b32 s1, s45, 1
	s_and_b32 s0, s0, 0x7c0
	s_waitcnt lgkmcnt(0)
	s_and_b32 s1, s1, 0x1fc0
	v_add_u32_e32 v36, s0, v8
	ds_read2_b32 v[2:3], v13 offset1:65
	s_add_i32 s6, s1, 0xffffeb00
	v_ashrrev_i32_e32 v37, 31, v36
	s_waitcnt lgkmcnt(0)
; __device__ __forceinline__ unsigned cvt_pk_bf16(float lo, float hi) { unsigned r; asm volatile("v_cvt_pk_bf16_f32 %0, %1, %2" : "=v"(r) : "v"(lo), "v"(hi)); return r; }
; #define LAS __attribute__((address_space(3)))
; #define LDS_WAIT() asm volatile("s_waitcnt lgkmcnt(0)" ::: "memory")
; __device__ __forceinline__ void transpose_item(const float* __restrict__ W, int N, int src_n0, int n_valid, bf16_t* __restrict__ WT, int Kd, int dst_row0, int k0, ...
;     ...
;     const int c8 = lane & 7;
; #pragma unroll
;     for (int j = 0; j < 8; ++j) { const int n = (lane >> 3) + 8 * j; const LAS float* s = scr + (8 * c8) * 65 + n;
;         const float sc = (scale != nullptr && n < n_valid) ? scale[src_n0 + n] : 1.f;
;         float ks[8];
; #pragma unroll
;         for (int i = 0; i < 8; ++i) ks[i] = (kscale != nullptr) ? kscale[k0 + 8 * c8 + i] * sc : sc;
;         u32x4 o; o.x = cvt_pk_bf16(s[0 * 65] * ks[0], s[1 * 65] * ks[1]); o.y = cvt_pk_bf16(s[2 * 65] * ks[2], s[3 * 65] * ks[3]); o.z = cvt_pk_bf16(s[4 * 65] * ks[4], s[5 * 65] * ks[5]); o.w = cvt_pk_bf16(s[6 * 65] * ks[6], s[7 * 65] * ks[7]);
;         *(u32x4*)(WT + (size_t)(dst_row0 + n) * Kd + k0 + 8 * c8) = o; }
;     LDS_WAIT();
	v_cvt_pk_bf16_f32 v2, v2, v3
	ds_read2_b32 v[4:5], v13 offset0:130 offset1:195
	v_add_u32_e32 v14, 0x400, v13
	v_lshl_add_u64 v[58:59], s[6:7], 1, v[20:21]
	v_lshlrev_b64 v[36:37], 12, v[36:37]
	s_waitcnt lgkmcnt(0)
	v_cvt_pk_bf16_f32 v3, v4, v5
	ds_read2_b32 v[4:5], v14 offset0:4 offset1:69
	v_lshl_add_u64 v[36:37], v[58:59], 0, v[36:37]
	s_waitcnt lgkmcnt(0)
	v_cvt_pk_bf16_f32 v4, v4, v5
	ds_read2_b32 v[6:7], v14 offset0:134 offset1:199
	s_waitcnt lgkmcnt(0)
	v_cvt_pk_bf16_f32 v5, v6, v7
	global_store_dwordx4 v[36:37], v[2:5], off
	v_add_u32_e32 v36, s0, v38
	v_ashrrev_i32_e32 v37, 31, v36
	ds_read2_b32 v[6:7], v13 offset0:8 offset1:73
	s_waitcnt lgkmcnt(0)
	v_cvt_pk_bf16_f32 v2, v6, v7
	ds_read2_b32 v[4:5], v13 offset0:138 offset1:203
	v_lshlrev_b64 v[36:37], 12, v[36:37]
	s_waitcnt lgkmcnt(0)
	v_cvt_pk_bf16_f32 v3, v4, v5
	ds_read2_b32 v[4:5], v14 offset0:12 offset1:77
	v_lshl_add_u64 v[36:37], v[58:59], 0, v[36:37]
	s_waitcnt lgkmcnt(0)
	v_cvt_pk_bf16_f32 v4, v4, v5
	ds_read2_b32 v[6:7], v14 offset0:142 offset1:207
	s_waitcnt lgkmcnt(0)
	v_cvt_pk_bf16_f32 v5, v6, v7
	global_store_dwordx4 v[36:37], v[2:5], off
	v_add_u32_e32 v36, s0, v39
	v_ashrrev_i32_e32 v37, 31, v36
	ds_read2_b32 v[6:7], v13 offset0:16 offset1:81
	s_waitcnt lgkmcnt(0)
	v_cvt_pk_bf16_f32 v2, v6, v7
	ds_read2_b32 v[4:5], v13 offset0:146 offset1:211
	v_lshlrev_b64 v[36:37], 12, v[36:37]
	s_waitcnt lgkmcnt(0)
	v_cvt_pk_bf16_f32 v3, v4, v5
	ds_read2_b32 v[4:5], v14 offset0:20 offset1:85
	v_lshl_add_u64 v[36:37], v[58:59], 0, v[36:37]
	s_waitcnt lgkmcnt(0)
	v_cvt_pk_bf16_f32 v4, v4, v5
	ds_read2_b32 v[6:7], v14 offset0:150 offset1:215
	s_waitcnt lgkmcnt(0)
	v_cvt_pk_bf16_f32 v5, v6, v7
	global_store_dwordx4 v[36:37], v[2:5], off
	v_add_u32_e32 v36, s0, v40
	v_ashrrev_i32_e32 v37, 31, v36
	ds_read2_b32 v[6:7], v13 offset0:24 offset1:89
	s_waitcnt lgkmcnt(0)
	v_cvt_pk_bf16_f32 v2, v6, v7
	ds_read2_b32 v[4:5], v13 offset0:154 offset1:219
	v_lshlrev_b64 v[36:37], 12, v[36:37]
	s_waitcnt lgkmcnt(0)
	v_cvt_pk_bf16_f32 v3, v4, v5
	ds_read2_b32 v[4:5], v14 offset0:28 offset1:93
	v_lshl_add_u64 v[36:37], v[58:59], 0, v[36:37]
	s_waitcnt lgkmcnt(0)
	v_cvt_pk_bf16_f32 v4, v4, v5
	ds_read2_b32 v[6:7], v14 offset0:158 offset1:223
	s_waitcnt lgkmcnt(0)
	v_cvt_pk_bf16_f32 v5, v6, v7
	global_store_dwordx4 v[36:37], v[2:5], off
	v_add_u32_e32 v36, s0, v41
	v_ashrrev_i32_e32 v37, 31, v36
	ds_read2_b32 v[6:7], v13 offset0:32 offset1:97
	s_waitcnt lgkmcnt(0)
	v_cvt_pk_bf16_f32 v2, v6, v7
	ds_read2_b32 v[4:5], v13 offset0:162 offset1:227
	v_lshlrev_b64 v[36:37], 12, v[36:37]
	s_waitcnt lgkmcnt(0)
	v_cvt_pk_bf16_f32 v3, v4, v5
	ds_read2_b32 v[4:5], v14 offset0:36 offset1:101
	v_lshl_add_u64 v[36:37], v[58:59], 0, v[36:37]
	s_waitcnt lgkmcnt(0)
	v_cvt_pk_bf16_f32 v4, v4, v5
	ds_read2_b32 v[6:7], v14 offset0:166 offset1:231
	s_waitcnt lgkmcnt(0)
	v_cvt_pk_bf16_f32 v5, v6, v7
	global_store_dwordx4 v[36:37], v[2:5], off
	v_add_u32_e32 v36, s0, v42
	v_ashrrev_i32_e32 v37, 31, v36
	ds_read2_b32 v[6:7], v13 offset0:40 offset1:105
	s_waitcnt lgkmcnt(0)
	v_cvt_pk_bf16_f32 v2, v6, v7
	ds_read2_b32 v[4:5], v13 offset0:170 offset1:235
	v_lshlrev_b64 v[36:37], 12, v[36:37]
	s_waitcnt lgkmcnt(0)
	v_cvt_pk_bf16_f32 v3, v4, v5
	ds_read2_b32 v[4:5], v14 offset0:44 offset1:109
	v_lshl_add_u64 v[36:37], v[58:59], 0, v[36:37]
	s_waitcnt lgkmcnt(0)
	v_cvt_pk_bf16_f32 v4, v4, v5
	ds_read2_b32 v[6:7], v14 offset0:174 offset1:239
	s_waitcnt lgkmcnt(0)
	v_cvt_pk_bf16_f32 v5, v6, v7
	global_store_dwordx4 v[36:37], v[2:5], off
	v_add_u32_e32 v36, s0, v43
	ds_read2_b32 v[6:7], v13 offset0:48 offset1:113
	s_waitcnt lgkmcnt(0)
	v_cvt_pk_bf16_f32 v2, v6, v7
	ds_read2_b32 v[4:5], v13 offset0:178 offset1:243
	v_ashrrev_i32_e32 v37, 31, v36
	s_waitcnt lgkmcnt(0)
	v_cvt_pk_bf16_f32 v3, v4, v5
	ds_read2_b32 v[4:5], v14 offset0:52 offset1:117
	v_lshlrev_b64 v[36:37], 12, v[36:37]
	s_waitcnt lgkmcnt(0)
	v_cvt_pk_bf16_f32 v4, v4, v5
	ds_read2_b32 v[6:7], v14 offset0:182 offset1:247
	s_waitcnt lgkmcnt(0)
	v_cvt_pk_bf16_f32 v5, v6, v7
	v_lshl_add_u64 v[36:37], v[58:59], 0, v[36:37]
	ds_read2_b32 v[6:7], v13 offset0:56 offset1:121
	global_store_dwordx4 v[36:37], v[2:5], off
	v_add_u32_e32 v36, s0, v44
	v_ashrrev_i32_e32 v37, 31, v36
	s_waitcnt lgkmcnt(0)
	v_cvt_pk_bf16_f32 v2, v6, v7
	ds_read2_b32 v[4:5], v13 offset0:186 offset1:251
	s_waitcnt lgkmcnt(0)
	v_cvt_pk_bf16_f32 v3, v4, v5
	ds_read2_b32 v[4:5], v14 offset0:60 offset1:125
	s_waitcnt lgkmcnt(0)
	v_cvt_pk_bf16_f32 v4, v4, v5
	ds_read2_b32 v[6:7], v14 offset0:190 offset1:255
	v_lshlrev_b64 v[36:37], 12, v[36:37]
	s_waitcnt lgkmcnt(0)
	v_cvt_pk_bf16_f32 v5, v6, v7
	v_lshl_add_u64 v[6:7], v[58:59], 0, v[36:37]
	global_store_dwordx4 v[6:7], v[2:5], off
	s_waitcnt lgkmcnt(0)

; __device__ __forceinline__ unsigned cvt_pk_bf16(float lo, float hi) { unsigned r; asm volatile("v_cvt_pk_bf16_f32 %0, %1, %2" : "=v"(r) : "v"(lo), "v"(hi)); return r; }
; __device__ __forceinline__ void rmsnorm_row(const float* __restrict__ xrow, const float* __restrict__ g, bf16_t* __restrict__ orow, int lane) {
;     const f32x4* xr = (const f32x4*)xrow + lane; f32x4 v[8]; float s = 0.f;
; #pragma unroll
;     for (int j = 0; j < 8; ++j) { v[j] = xr[64 * j]; s += (v[j].x * v[j].x + v[j].y * v[j].y) + (v[j].z * v[j].z + v[j].w * v[j].w); }
;     const float r = 1.f / sqrtf(wave_sum(s) * (1.f / D_) + EPS_);
;     const f32x4* gr = (const f32x4*)g + lane; u32x2* o8 = (u32x2*)orow + lane;
; #pragma unroll
;     for (int j = 0; j < 8; ++j) { const f32x4 gg = gr[64 * j]; u32x2 o; o.x = cvt_pk_bf16(v[j].x * r * gg.x, v[j].y * r * gg.y); o.y = cvt_pk_bf16(v[j].z * r * gg.z, v[j].w * r * gg.w); o8[64 * j] = o; }
; __global__ void __launch_bounds__(512, 2) mega(Params p) {
;     ...
;         for (int row = gw; row < S_; row += ngw) rmsnorm_row(x + (size_t)row * D_, attn_g, H + (size_t)row * D_, lane);
.LBB0_186:
	s_cmpk_lt_i32 s80, 0x4000
	s_cselect_b64 s[0:1], -1, 0
	v_writelane_b32 v248, s0, 4
	s_cmpk_gt_i32 s80, 0x3fff
	v_mbcnt_lo_u32_b32 v150, -1, 0
	v_writelane_b32 v248, s1, 5
	s_cbranch_scc1 .LBB0_189
	v_ashrrev_i32_e32 v11, 31, v10
	v_lshlrev_b64 v[6:7], 4, v[10:11]
	s_waitcnt lgkmcnt(0)
	v_lshl_add_u64 v[12:13], s[42:43], 0, v[6:7]
	global_load_dwordx4 v[2:5], v[12:13], off
	v_mbcnt_hi_u32_b32 v8, -1, v150
	v_and_b32_e32 v9, 64, v8
	v_add_u32_e32 v9, 64, v9
	v_xor_b32_e32 v14, 1, v8
	v_cmp_lt_i32_e32 vcc, v14, v9
	s_ashr_i32 s81, s80, 31
	s_lshl_b64 s[6:7], s[80:81], 12
	v_cndmask_b32_e32 v14, v8, v14, vcc
	v_lshlrev_b32_e32 v26, 2, v14
	v_xor_b32_e32 v14, 2, v8
	v_cmp_lt_i32_e32 vcc, v14, v9
	s_add_u32 s6, s60, s6
	s_addc_u32 s7, s61, s7
	v_cndmask_b32_e32 v14, v8, v14, vcc
	v_lshlrev_b32_e32 v27, 2, v14
	v_xor_b32_e32 v14, 4, v8
	v_cmp_lt_i32_e32 vcc, v14, v9
	s_ashr_i32 s83, s82, 31
	s_mov_b64 s[0:1], 0x1000
	v_cndmask_b32_e32 v14, v8, v14, vcc
	v_lshlrev_b32_e32 v28, 2, v14
	v_xor_b32_e32 v14, 8, v8
	v_cmp_lt_i32_e32 vcc, v14, v9
	s_lshl_b64 s[8:9], s[80:81], 13
	s_mov_b32 s3, 0xf800000
	v_cndmask_b32_e32 v14, v8, v14, vcc
	v_lshlrev_b32_e32 v29, 2, v14
	v_xor_b32_e32 v14, 16, v8
	v_cmp_lt_i32_e32 vcc, v14, v9
	v_mov_b32_e32 v32, 0x260
	s_mov_b32 s10, s80
	v_cndmask_b32_e32 v14, v8, v14, vcc
	v_lshlrev_b32_e32 v30, 2, v14
	v_xor_b32_e32 v14, 32, v8
	v_cmp_lt_i32_e32 vcc, v14, v9
	s_nop 1
	v_cndmask_b32_e32 v8, v8, v14, vcc
	v_lshlrev_b32_e32 v31, 2, v8
	v_lshl_add_u64 v[8:9], v[10:11], 3, s[6:7]
	s_mov_b64 s[6:7], 0x5f82e00
	v_lshl_add_u64 v[22:23], v[8:9], 0, s[6:7]
	s_lshl_b64 s[6:7], s[82:83], 12
	v_lshl_add_u64 v[14:15], v[12:13], 0, s[0:1]
	s_mov_b64 s[0:1], 0x1400
	s_add_u32 s8, s40, s8
	v_lshl_add_u64 v[16:17], v[12:13], 0, s[0:1]
	s_mov_b64 s[0:1], 0x1800
	s_addc_u32 s9, s41, s9
	v_lshl_add_u64 v[18:19], v[12:13], 0, s[0:1]
	s_mov_b64 s[0:1], 0x1c00
	v_lshl_add_u64 v[6:7], s[8:9], 0, v[6:7]
	v_lshl_add_u64 v[20:21], v[12:13], 0, s[0:1]
	v_lshl_add_u64 v[24:25], v[6:7], 0, s[0:1]
	s_lshl_b64 s[8:9], s[82:83], 13
	v_mov_b32_e32 v11, 0x358637bd
	global_load_dwordx4 v[152:155], v[12:13], off offset:1024
	global_load_dwordx4 v[156:159], v[12:13], off offset:2048
	global_load_dwordx4 v[160:163], v[12:13], off offset:3072
	global_load_dwordx4 v[164:167], v[14:15], off
	global_load_dwordx4 v[168:171], v[16:17], off
	global_load_dwordx4 v[172:175], v[18:19], off
	global_load_dwordx4 v[176:179], v[20:21], off
; __device__ __forceinline__ unsigned cvt_pk_bf16(float lo, float hi) { unsigned r; asm volatile("v_cvt_pk_bf16_f32 %0, %1, %2" : "=v"(r) : "v"(lo), "v"(hi)); return r; }
; __device__ __forceinline__ void rmsnorm_row(const float* __restrict__ xrow, const float* __restrict__ g, bf16_t* __restrict__ orow, int lane) {
;     const f32x4* xr = (const f32x4*)xrow + lane; f32x4 v[8]; float s = 0.f;
; #pragma unroll
;     for (int j = 0; j < 8; ++j) { v[j] = xr[64 * j]; s += (v[j].x * v[j].x + v[j].y * v[j].y) + (v[j].z * v[j].z + v[j].w * v[j].w); }
;     const float r = 1.f / sqrtf(wave_sum(s) * (1.f / D_) + EPS_);
;     const f32x4* gr = (const f32x4*)g + lane; u32x2* o8 = (u32x2*)orow + lane;
; #pragma unroll
;     for (int j = 0; j < 8; ++j) { const f32x4 gg = gr[64 * j]; u32x2 o; o.x = cvt_pk_bf16(v[j].x * r * gg.x, v[j].y * r * gg.y); o.y = cvt_pk_bf16(v[j].z * r * gg.z, v[j].w * r * gg.w); o8[64 * j] = o; }
.LBB0_188:
	v_add_co_u32_e32 v62, vcc, 0xfffff000, v24
	global_load_dwordx4 v[34:37], v[24:25], off offset:-3072
	global_load_dwordx4 v[38:41], v[24:25], off offset:-2048
	global_load_dwordx4 v[42:45], v[24:25], off offset:-1024
	global_load_dwordx4 v[6:9], v[24:25], off
	v_addc_co_u32_e32 v63, vcc, -1, v25, vcc
	global_load_dwordx4 v[46:49], v[62:63], off offset:-3072
	global_load_dwordx4 v[50:53], v[62:63], off offset:-2048
	global_load_dwordx4 v[54:57], v[62:63], off offset:-1024
	global_load_dwordx4 v[58:61], v[24:25], off offset:-4096
	s_add_i32 s10, s10, s82
	s_cmpk_gt_i32 s10, 0x3fff
	v_lshl_add_u64 v[24:25], v[24:25], 0, s[8:9]
	s_waitcnt vmcnt(7)
	v_mul_f32_e32 v33, v35, v35
	v_mul_f32_e32 v62, v37, v37
	s_waitcnt vmcnt(6)
	v_mul_f32_e32 v63, v39, v39
	v_mul_f32_e32 v64, v41, v41
	s_waitcnt vmcnt(5)
	v_mul_f32_e32 v65, v43, v43
	v_mul_f32_e32 v66, v45, v45
	s_waitcnt vmcnt(3)
	v_mul_f32_e32 v69, v47, v47
	v_mul_f32_e32 v70, v49, v49
	s_waitcnt vmcnt(2)
	v_mul_f32_e32 v71, v51, v51
	v_mul_f32_e32 v72, v53, v53
	v_mul_f32_e32 v67, v7, v7
	v_mul_f32_e32 v68, v9, v9
	v_fmac_f32_e32 v33, v34, v34
	v_fmac_f32_e32 v62, v36, v36
	v_fmac_f32_e32 v63, v38, v38
	v_fmac_f32_e32 v64, v40, v40
	v_fmac_f32_e32 v65, v42, v42
	v_fmac_f32_e32 v66, v44, v44
	s_waitcnt vmcnt(1)
	v_mul_f32_e32 v73, v55, v55
	v_mul_f32_e32 v74, v57, v57
	v_fmac_f32_e32 v69, v46, v46
	v_fmac_f32_e32 v70, v48, v48
	v_fmac_f32_e32 v71, v50, v50
	v_fmac_f32_e32 v72, v52, v52
	v_fmac_f32_e32 v67, v6, v6
	v_fmac_f32_e32 v68, v8, v8
	s_waitcnt vmcnt(0)
	v_mul_f32_e32 v75, v59, v59
	v_mul_f32_e32 v76, v61, v61
	v_add_f32_e32 v33, v33, v62
	v_add_f32_e32 v62, v63, v64
	v_add_f32_e32 v63, v65, v66
	v_fmac_f32_e32 v73, v54, v54
	v_fmac_f32_e32 v74, v56, v56
	v_add_f32_e32 v65, v69, v70
	v_add_f32_e32 v66, v71, v72
	v_add_f32_e32 v64, v67, v68
	v_fmac_f32_e32 v75, v58, v58
	v_fmac_f32_e32 v76, v60, v60
	v_add_f32_e32 v67, v73, v74
	v_add_f32_e32 v65, v65, v66
	v_add_f32_e32 v68, v75, v76
	v_add_f32_e32 v65, v65, v67
	v_add_f32_e32 v65, v65, v68
	v_add_f32_e32 v33, v65, v33
	v_add_f32_e32 v33, v33, v62
	v_add_f32_e32 v33, v33, v63
	v_add_f32_e32 v33, v33, v64
	ds_bpermute_b32 v62, v26, v33
	s_waitcnt lgkmcnt(0)
	v_add_f32_e32 v33, v33, v62
	ds_bpermute_b32 v62, v27, v33
	s_waitcnt lgkmcnt(0)
	v_add_f32_e32 v33, v33, v62
	ds_bpermute_b32 v62, v28, v33
	s_waitcnt lgkmcnt(0)
	v_add_f32_e32 v33, v33, v62
	ds_bpermute_b32 v62, v29, v33
	s_waitcnt lgkmcnt(0)
	v_add_f32_e32 v33, v33, v62
	ds_bpermute_b32 v62, v30, v33
	s_waitcnt lgkmcnt(0)
	v_add_f32_e32 v33, v33, v62
	ds_bpermute_b32 v62, v31, v33
	s_waitcnt lgkmcnt(0)
	v_add_f32_e32 v33, v33, v62
	v_fmamk_f32 v33, v33, 0x3a000000, v11
	v_mul_f32_e32 v62, 0x4f800000, v33
	v_cmp_gt_f32_e32 vcc, s3, v33
	s_nop 1
	v_cndmask_b32_e32 v33, v33, v62, vcc
	v_sqrt_f32_e32 v62, v33
	s_nop 0
	v_add_u32_e32 v63, -1, v62
	v_add_u32_e32 v64, 1, v62
	v_fma_f32 v65, -v63, v62, v33
	v_fma_f32 v66, -v64, v62, v33
	v_cmp_ge_f32_e64 s[0:1], 0, v65
	s_nop 1
	v_cndmask_b32_e64 v62, v62, v63, s[0:1]
	v_cmp_lt_f32_e64 s[0:1], 0, v66
	s_nop 1
	v_cndmask_b32_e64 v62, v62, v64, s[0:1]
	v_mul_f32_e32 v63, 0x37800000, v62
	v_cndmask_b32_e32 v62, v62, v63, vcc
	v_cmp_class_f32_e32 vcc, v33, v32
	s_nop 1
	v_cndmask_b32_e32 v33, v62, v33, vcc
	v_div_scale_f32 v62, s[0:1], v33, v33, 1.0
	v_rcp_f32_e32 v64, v62
	v_div_scale_f32 v63, vcc, 1.0, v33, 1.0
	v_fma_f32 v65, -v62, v64, 1.0
	v_fmac_f32_e32 v64, v65, v64
	v_mul_f32_e32 v65, v63, v64
	v_fma_f32 v66, -v62, v65, v63
	v_fmac_f32_e32 v65, v66, v64
	v_fma_f32 v62, -v62, v65, v63
	v_div_fmas_f32 v62, v62, v64, v65
	v_div_fixup_f32 v33, v62, v33, 1.0
	v_mul_f32_e32 v46, v46, v33
	v_mul_f32_e32 v47, v47, v33
	v_mul_f32_e32 v48, v48, v33
	v_mul_f32_e32 v49, v49, v33
	v_mul_f32_e32 v46, v2, v46
	v_mul_f32_e32 v47, v3, v47
	v_mul_f32_e32 v48, v4, v48
	v_mul_f32_e32 v49, v5, v49
	v_cvt_pk_bf16_f32 v62, v46, v47
	v_cvt_pk_bf16_f32 v63, v48, v49
	v_mul_f32_e32 v50, v50, v33
	v_mul_f32_e32 v51, v51, v33
	v_mul_f32_e32 v52, v52, v33
	v_mul_f32_e32 v53, v53, v33
	global_store_dwordx2 v[22:23], v[62:63], off offset:-3584
	v_mul_f32_e32 v34, v34, v33
	v_mul_f32_e32 v35, v35, v33
	v_mul_f32_e32 v36, v36, v33
	v_mul_f32_e32 v37, v37, v33
	v_mul_f32_e32 v38, v38, v33
	v_mul_f32_e32 v39, v39, v33
	v_mul_f32_e32 v40, v40, v33
	v_mul_f32_e32 v41, v41, v33
	v_mul_f32_e32 v6, v6, v33
	v_mul_f32_e32 v7, v7, v33
	v_mul_f32_e32 v8, v8, v33
	v_mul_f32_e32 v9, v9, v33
	v_mul_f32_e32 v46, v152, v50
	v_mul_f32_e32 v47, v153, v51
	v_mul_f32_e32 v48, v154, v52
	v_mul_f32_e32 v49, v155, v53
	v_cvt_pk_bf16_f32 v50, v46, v47
	v_cvt_pk_bf16_f32 v51, v48, v49
	v_mul_f32_e32 v52, v54, v33
	v_mul_f32_e32 v53, v55, v33
	v_mul_f32_e32 v54, v56, v33
	v_mul_f32_e32 v55, v57, v33
	global_store_dwordx2 v[22:23], v[50:51], off offset:-3072
	v_mul_f32_e32 v46, v52, v156
	v_mul_f32_e32 v47, v53, v157
	v_mul_f32_e32 v48, v54, v158
	v_mul_f32_e32 v49, v55, v159
	v_cvt_pk_bf16_f32 v50, v46, v47
	v_cvt_pk_bf16_f32 v51, v48, v49
	v_mul_f32_e32 v52, v58, v33
	v_mul_f32_e32 v53, v59, v33
	v_mul_f32_e32 v54, v60, v33
	v_mul_f32_e32 v55, v61, v33
	global_store_dwordx2 v[22:23], v[50:51], off offset:-2560
	v_mul_f32_e32 v46, v52, v160
	v_mul_f32_e32 v47, v53, v161
	v_mul_f32_e32 v48, v54, v162
	v_mul_f32_e32 v49, v55, v163
	v_cvt_pk_bf16_f32 v50, v46, v47
	v_cvt_pk_bf16_f32 v51, v48, v49
	v_mul_f32_e32 v34, v34, v164
	v_mul_f32_e32 v35, v35, v165
	v_mul_f32_e32 v36, v36, v166
	v_mul_f32_e32 v37, v37, v167
	global_store_dwordx2 v[22:23], v[50:51], off offset:-2048
	v_cvt_pk_bf16_f32 v46, v34, v35
	v_cvt_pk_bf16_f32 v47, v36, v37
	v_mul_f32_e32 v34, v38, v168
	v_mul_f32_e32 v35, v39, v169
	v_mul_f32_e32 v36, v40, v170
	v_mul_f32_e32 v37, v41, v171
	global_store_dwordx2 v[22:23], v[46:47], off offset:-1536
	v_cvt_pk_bf16_f32 v38, v34, v35
	v_cvt_pk_bf16_f32 v39, v36, v37
	v_mul_f32_e32 v40, v42, v33
	v_mul_f32_e32 v41, v43, v33
	v_mul_f32_e32 v42, v44, v33
	v_mul_f32_e32 v43, v45, v33
	global_store_dwordx2 v[22:23], v[38:39], off offset:-1024
	v_mul_f32_e32 v34, v40, v172
	v_mul_f32_e32 v35, v41, v173
	v_mul_f32_e32 v36, v42, v174
	v_mul_f32_e32 v37, v43, v175
	v_cvt_pk_bf16_f32 v38, v34, v35
	v_cvt_pk_bf16_f32 v39, v36, v37
	v_mul_f32_e32 v6, v6, v176
	v_mul_f32_e32 v7, v7, v177
	global_store_dwordx2 v[22:23], v[38:39], off offset:-512
	v_mul_f32_e32 v8, v8, v178
	v_mul_f32_e32 v9, v9, v179
	v_cvt_pk_bf16_f32 v6, v6, v7
	v_cvt_pk_bf16_f32 v7, v8, v9
	global_store_dwordx2 v[22:23], v[6:7], off
	v_lshl_add_u64 v[22:23], v[22:23], 0, s[6:7]
	s_cbranch_scc0 .LBB0_188
	s_nop 0
